# EpiUp epilogue (VALU-bound): 64 dead zero-init v_mov ahead of full-mask row_ror DPP movs deleted
# speedup vs baseline: 1.0056x; 1.0001x over previous
.LBB0_173:
	s_add_u32 s64, s62, 0x100
	s_addc_u32 s65, s63, 0
	s_add_i32 s34, 0, 0x10000
	v_add_u32_e32 v108, s34, v196
	ds_read_b128 v[96:99], v108
	ds_read_b128 v[100:103], v108 offset:1024
	ds_read_b128 v[104:107], v108 offset:2048
	ds_read_b128 v[158:161], v108 offset:3072
	s_cmp_eq_u32 s83, 28
	s_cselect_b32 s69, s57, s65
	s_cselect_b32 s68, s71, s64
	s_cselect_b32 s67, s55, s82
	s_cselect_b32 s66, s80, s81
	v_lshl_add_u64 v[108:109], s[62:63], 0, v[154:155]
	s_add_i32 m0, s44, 0xc000
	ds_read_b128 v[162:165], v207
	ds_read_b128 v[166:169], v207 offset:1024
	ds_read_b128 v[170:173], v207 offset:2048
	ds_read_b128 v[180:183], v207 offset:3072
	ds_read_b128 v[184:187], v207 offset:4096
	ds_read_b128 v[188:191], v207 offset:5120
	ds_read_b128 v[192:195], v207 offset:6144
	ds_read_b128 v[198:201], v207 offset:7168
	global_load_lds_dwordx4 v[108:109], off
	v_lshl_add_u64 v[108:109], s[62:63], 0, v[156:157]
	s_add_i32 m0, s44, 0xe000
	s_nop 0
	global_load_lds_dwordx4 v[108:109], off
	s_waitcnt lgkmcnt(8)
	s_barrier
	s_waitcnt lgkmcnt(0)
	v_mfma_f32_16x16x32_bf16 v[138:141], v[96:99], v[162:165], v[138:141]
	v_mfma_f32_16x16x32_bf16 v[60:63], v[104:107], v[162:165], v[60:63]
	v_mfma_f32_16x16x32_bf16 v[134:137], v[96:99], v[170:173], v[134:137]
	v_mfma_f32_16x16x32_bf16 v[56:59], v[104:107], v[170:173], v[56:59]
	v_mfma_f32_16x16x32_bf16 v[130:133], v[96:99], v[184:187], v[130:133]
	v_mfma_f32_16x16x32_bf16 v[52:55], v[104:107], v[184:187], v[52:55]
	v_mfma_f32_16x16x32_bf16 v[126:129], v[96:99], v[192:195], v[126:129]
	v_mfma_f32_16x16x32_bf16 v[48:51], v[104:107], v[192:195], v[48:51]
	v_mfma_f32_16x16x32_bf16 v[138:141], v[100:103], v[166:169], v[138:141]
	v_mfma_f32_16x16x32_bf16 v[60:63], v[158:161], v[166:169], v[60:63]
	v_mfma_f32_16x16x32_bf16 v[134:137], v[100:103], v[180:183], v[134:137]
	v_mfma_f32_16x16x32_bf16 v[56:59], v[158:161], v[180:183], v[56:59]
	v_mfma_f32_16x16x32_bf16 v[130:133], v[100:103], v[188:191], v[130:133]
	v_mfma_f32_16x16x32_bf16 v[52:55], v[158:161], v[188:191], v[52:55]
	v_mfma_f32_16x16x32_bf16 v[126:129], v[100:103], v[198:201], v[126:129]
	v_mfma_f32_16x16x32_bf16 v[48:51], v[158:161], v[198:201], v[48:51]
	s_barrier
	s_add_i32 s35, 0, 0x14000
	s_add_i32 s34, s34, s39
	v_add_u32_e32 v108, s35, v196
	v_lshl_add_u64 v[174:175], s[66:67], 0, v[146:147]
	s_mov_b32 m0, s34
	ds_read_b128 v[208:211], v108
	ds_read_b128 v[212:215], v108 offset:1024
	ds_read_b128 v[216:219], v108 offset:2048
	ds_read_b128 v[220:223], v108 offset:3072
	global_load_lds_dwordx4 v[174:175], off
	v_lshl_add_u64 v[224:225], s[66:67], 0, v[142:143]
	s_add_i32 m0, s34, 0x2000
	s_nop 0
	global_load_lds_dwordx4 v[224:225], off
	s_barrier
	s_waitcnt lgkmcnt(0)
	v_mfma_f32_16x16x32_bf16 v[122:125], v[208:211], v[162:165], v[122:125]
	v_mfma_f32_16x16x32_bf16 v[44:47], v[216:219], v[162:165], v[44:47]
	v_mfma_f32_16x16x32_bf16 v[114:117], v[208:211], v[170:173], v[114:117]
	v_mfma_f32_16x16x32_bf16 v[36:39], v[216:219], v[170:173], v[36:39]
	v_mfma_f32_16x16x32_bf16 v[118:121], v[208:211], v[184:187], v[118:121]
	v_mfma_f32_16x16x32_bf16 v[40:43], v[216:219], v[184:187], v[40:43]
	v_mfma_f32_16x16x32_bf16 v[108:111], v[208:211], v[192:195], v[110:113]
	v_mfma_f32_16x16x32_bf16 v[32:35], v[216:219], v[192:195], v[32:35]
	v_mfma_f32_16x16x32_bf16 v[122:125], v[212:215], v[166:169], v[122:125]
	v_mfma_f32_16x16x32_bf16 v[44:47], v[220:223], v[166:169], v[44:47]
	v_mfma_f32_16x16x32_bf16 v[114:117], v[212:215], v[180:183], v[114:117]
	v_mfma_f32_16x16x32_bf16 v[36:39], v[220:223], v[180:183], v[36:39]
	v_mfma_f32_16x16x32_bf16 v[118:121], v[212:215], v[188:191], v[118:121]
	v_mfma_f32_16x16x32_bf16 v[40:43], v[220:223], v[188:191], v[40:43]
	v_mfma_f32_16x16x32_bf16 v[108:111], v[212:215], v[198:201], v[108:111]
	v_mfma_f32_16x16x32_bf16 v[32:35], v[220:223], v[198:201], v[32:35]
	s_mov_b32 m0, s44
	v_lshl_add_u64 v[226:227], s[68:69], 0, v[148:149]
	s_barrier
	ds_read_b128 v[162:165], v207 offset:16384
	ds_read_b128 v[166:169], v207 offset:17408
	ds_read_b128 v[170:173], v207 offset:18432
	ds_read_b128 v[180:183], v207 offset:19456
	ds_read_b128 v[184:187], v207 offset:20480
	ds_read_b128 v[188:191], v207 offset:21504
	ds_read_b128 v[192:195], v207 offset:22528
	ds_read_b128 v[198:201], v207 offset:23552
	global_load_lds_dwordx4 v[226:227], off
	v_lshl_add_u64 v[228:229], s[68:69], 0, v[144:145]
	s_mov_b32 m0, s72
	s_nop 0
	global_load_lds_dwordx4 v[228:229], off
	s_barrier
	s_waitcnt lgkmcnt(0)
	v_mfma_f32_16x16x32_bf16 v[92:95], v[96:99], v[162:165], v[92:95]
	v_mfma_f32_16x16x32_bf16 v[28:31], v[104:107], v[162:165], v[28:31]
	v_mfma_f32_16x16x32_bf16 v[88:91], v[96:99], v[170:173], v[88:91]
	v_mfma_f32_16x16x32_bf16 v[24:27], v[104:107], v[170:173], v[24:27]
	v_mfma_f32_16x16x32_bf16 v[84:87], v[96:99], v[184:187], v[84:87]
	v_mfma_f32_16x16x32_bf16 v[20:23], v[104:107], v[184:187], v[20:23]
	v_mfma_f32_16x16x32_bf16 v[80:83], v[96:99], v[192:195], v[80:83]
	v_mfma_f32_16x16x32_bf16 v[16:19], v[104:107], v[192:195], v[16:19]
	v_mfma_f32_16x16x32_bf16 v[92:95], v[100:103], v[166:169], v[92:95]
	v_mfma_f32_16x16x32_bf16 v[28:31], v[158:161], v[166:169], v[28:31]
	v_mfma_f32_16x16x32_bf16 v[88:91], v[100:103], v[180:183], v[88:91]
	v_mfma_f32_16x16x32_bf16 v[24:27], v[158:161], v[180:183], v[24:27]
	v_mfma_f32_16x16x32_bf16 v[84:87], v[100:103], v[188:191], v[84:87]
	v_mfma_f32_16x16x32_bf16 v[20:23], v[158:161], v[188:191], v[20:23]
	v_mfma_f32_16x16x32_bf16 v[80:83], v[100:103], v[198:201], v[80:83]
	v_mfma_f32_16x16x32_bf16 v[16:19], v[158:161], v[198:201], v[16:19]
	s_barrier
	s_add_u32 s62, s66, 0x80000
	s_addc_u32 s63, s67, 0
	s_add_i32 s34, s35, s39
	v_lshl_add_u64 v[96:97], s[62:63], 0, v[146:147]
	s_mov_b32 m0, s34
	s_nop 0
	global_load_lds_dwordx4 v[96:97], off
	v_lshl_add_u64 v[96:97], s[62:63], 0, v[142:143]
	s_add_i32 m0, s34, 0x2000
	s_nop 0
	global_load_lds_dwordx4 v[96:97], off
	s_waitcnt vmcnt(6)
	s_barrier
	v_mfma_f32_16x16x32_bf16 v[76:79], v[208:211], v[162:165], v[76:79]
	v_mfma_f32_16x16x32_bf16 v[12:15], v[216:219], v[162:165], v[12:15]
	v_mfma_f32_16x16x32_bf16 v[68:71], v[208:211], v[170:173], v[68:71]
	v_mfma_f32_16x16x32_bf16 v[4:7], v[216:219], v[170:173], v[4:7]
	v_mfma_f32_16x16x32_bf16 v[72:75], v[208:211], v[184:187], v[72:75]
	v_mfma_f32_16x16x32_bf16 v[8:11], v[216:219], v[184:187], v[8:11]
	v_mfma_f32_16x16x32_bf16 v[64:67], v[208:211], v[192:195], v[64:67]
	v_mfma_f32_16x16x32_bf16 v[0:3], v[216:219], v[192:195], v[0:3]
	v_mfma_f32_16x16x32_bf16 v[76:79], v[212:215], v[166:169], v[76:79]
	v_mfma_f32_16x16x32_bf16 v[12:15], v[220:223], v[166:169], v[12:15]
	v_mfma_f32_16x16x32_bf16 v[68:71], v[212:215], v[180:183], v[68:71]
	v_mfma_f32_16x16x32_bf16 v[4:7], v[220:223], v[180:183], v[4:7]
	v_mfma_f32_16x16x32_bf16 v[72:75], v[212:215], v[188:191], v[72:75]
	v_mfma_f32_16x16x32_bf16 v[8:11], v[220:223], v[188:191], v[8:11]
	v_mfma_f32_16x16x32_bf16 v[64:67], v[212:215], v[198:201], v[64:67]
	v_mfma_f32_16x16x32_bf16 v[0:3], v[220:223], v[198:201], v[0:3]
	s_add_i32 s34, 0, 0x18000
	v_add_u32_e32 v112, s34, v196
	s_barrier
	ds_read_b128 v[96:99], v112
	ds_read_b128 v[100:103], v112 offset:1024
	ds_read_b128 v[104:107], v112 offset:2048
	ds_read_b128 v[158:161], v112 offset:3072
	s_add_u32 s62, s68, 0x80000
	s_addc_u32 s63, s69, 0
	s_mov_b32 m0, s73
	v_lshl_add_u64 v[112:113], s[62:63], 0, v[148:149]
	ds_read_b128 v[162:165], v207 offset:32768
	ds_read_b128 v[166:169], v207 offset:33792
	ds_read_b128 v[170:173], v207 offset:34816
	ds_read_b128 v[180:183], v207 offset:35840
	ds_read_b128 v[184:187], v207 offset:36864
	ds_read_b128 v[188:191], v207 offset:37888
	ds_read_b128 v[192:195], v207 offset:38912
	ds_read_b128 v[198:201], v207 offset:39936
	global_load_lds_dwordx4 v[112:113], off
	v_lshl_add_u64 v[112:113], s[62:63], 0, v[144:145]
	s_mov_b32 m0, s74
	s_nop 0
	global_load_lds_dwordx4 v[112:113], off
	s_waitcnt lgkmcnt(8)
	s_barrier
	s_waitcnt lgkmcnt(0)
	v_mfma_f32_16x16x32_bf16 v[138:141], v[96:99], v[162:165], v[138:141]
	v_mfma_f32_16x16x32_bf16 v[60:63], v[104:107], v[162:165], v[60:63]
	v_mfma_f32_16x16x32_bf16 v[134:137], v[96:99], v[170:173], v[134:137]
	v_mfma_f32_16x16x32_bf16 v[56:59], v[104:107], v[170:173], v[56:59]
	v_mfma_f32_16x16x32_bf16 v[130:133], v[96:99], v[184:187], v[130:133]
	v_mfma_f32_16x16x32_bf16 v[52:55], v[104:107], v[184:187], v[52:55]
	v_mfma_f32_16x16x32_bf16 v[126:129], v[96:99], v[192:195], v[126:129]
	v_mfma_f32_16x16x32_bf16 v[48:51], v[104:107], v[192:195], v[48:51]
	v_mfma_f32_16x16x32_bf16 v[138:141], v[100:103], v[166:169], v[138:141]
	v_mfma_f32_16x16x32_bf16 v[60:63], v[158:161], v[166:169], v[60:63]
	v_mfma_f32_16x16x32_bf16 v[134:137], v[100:103], v[180:183], v[134:137]
	v_mfma_f32_16x16x32_bf16 v[56:59], v[158:161], v[180:183], v[56:59]
	v_mfma_f32_16x16x32_bf16 v[130:133], v[100:103], v[188:191], v[130:133]
	v_mfma_f32_16x16x32_bf16 v[52:55], v[158:161], v[188:191], v[52:55]
	v_mfma_f32_16x16x32_bf16 v[126:129], v[100:103], v[198:201], v[126:129]
	v_mfma_f32_16x16x32_bf16 v[48:51], v[158:161], v[198:201], v[48:51]
	s_barrier
	s_add_i32 s35, 0, 0x1c000
	v_add_u32_e32 v112, s35, v196
	s_add_i32 s34, s34, s39
	ds_read_b128 v[208:211], v112
	ds_read_b128 v[212:215], v112 offset:1024
	ds_read_b128 v[216:219], v112 offset:2048
	ds_read_b128 v[220:223], v112 offset:3072
	v_lshl_add_u64 v[112:113], v[174:175], 0, s[40:41]
	s_mov_b32 m0, s34
	s_nop 0
	global_load_lds_dwordx4 v[112:113], off
	v_lshl_add_u64 v[112:113], v[224:225], 0, s[40:41]
	s_add_i32 m0, s34, 0x2000
	s_nop 0
	global_load_lds_dwordx4 v[112:113], off
	s_barrier
	s_waitcnt lgkmcnt(0)
	v_mfma_f32_16x16x32_bf16 v[122:125], v[208:211], v[162:165], v[122:125]
	v_mfma_f32_16x16x32_bf16 v[44:47], v[216:219], v[162:165], v[44:47]
	v_mfma_f32_16x16x32_bf16 v[112:115], v[208:211], v[170:173], v[114:117]
	v_mfma_f32_16x16x32_bf16 v[36:39], v[216:219], v[170:173], v[36:39]
	v_mfma_f32_16x16x32_bf16 v[118:121], v[208:211], v[184:187], v[118:121]
	v_mfma_f32_16x16x32_bf16 v[40:43], v[216:219], v[184:187], v[40:43]
	v_mfma_f32_16x16x32_bf16 v[108:111], v[208:211], v[192:195], v[108:111]
	v_mfma_f32_16x16x32_bf16 v[32:35], v[216:219], v[192:195], v[32:35]
	v_mfma_f32_16x16x32_bf16 v[122:125], v[212:215], v[166:169], v[122:125]
	v_mfma_f32_16x16x32_bf16 v[44:47], v[220:223], v[166:169], v[44:47]
	v_mfma_f32_16x16x32_bf16 v[114:117], v[212:215], v[180:183], v[112:115]
	v_mfma_f32_16x16x32_bf16 v[36:39], v[220:223], v[180:183], v[36:39]
	v_mfma_f32_16x16x32_bf16 v[118:121], v[212:215], v[188:191], v[118:121]
	v_mfma_f32_16x16x32_bf16 v[40:43], v[220:223], v[188:191], v[40:43]
	v_mfma_f32_16x16x32_bf16 v[110:113], v[212:215], v[198:201], v[108:111]
	v_mfma_f32_16x16x32_bf16 v[32:35], v[220:223], v[198:201], v[32:35]
	s_barrier
	s_mov_b32 m0, s76
	v_lshl_add_u64 v[108:109], v[226:227], 0, s[40:41]
	ds_read_b128 v[162:165], v207 offset:49152
	ds_read_b128 v[166:169], v207 offset:50176
	ds_read_b128 v[170:173], v207 offset:51200
	ds_read_b128 v[180:183], v207 offset:52224
	ds_read_b128 v[184:187], v207 offset:53248
	ds_read_b128 v[188:191], v207 offset:54272
	ds_read_b128 v[192:195], v207 offset:55296
	ds_read_b128 v[198:201], v207 offset:56320
	global_load_lds_dwordx4 v[108:109], off
	v_lshl_add_u64 v[108:109], v[228:229], 0, s[40:41]
	s_mov_b32 m0, s77
	s_nop 0
	global_load_lds_dwordx4 v[108:109], off
	s_barrier
	s_waitcnt lgkmcnt(0)
	v_mfma_f32_16x16x32_bf16 v[92:95], v[96:99], v[162:165], v[92:95]
	v_mfma_f32_16x16x32_bf16 v[28:31], v[104:107], v[162:165], v[28:31]
	v_mfma_f32_16x16x32_bf16 v[88:91], v[96:99], v[170:173], v[88:91]
	v_mfma_f32_16x16x32_bf16 v[24:27], v[104:107], v[170:173], v[24:27]
	v_mfma_f32_16x16x32_bf16 v[84:87], v[96:99], v[184:187], v[84:87]
	v_mfma_f32_16x16x32_bf16 v[20:23], v[104:107], v[184:187], v[20:23]
	v_mfma_f32_16x16x32_bf16 v[80:83], v[96:99], v[192:195], v[80:83]
	v_mfma_f32_16x16x32_bf16 v[16:19], v[104:107], v[192:195], v[16:19]
	v_mfma_f32_16x16x32_bf16 v[92:95], v[100:103], v[166:169], v[92:95]
	v_mfma_f32_16x16x32_bf16 v[28:31], v[158:161], v[166:169], v[28:31]
	v_mfma_f32_16x16x32_bf16 v[88:91], v[100:103], v[180:183], v[88:91]
	v_mfma_f32_16x16x32_bf16 v[24:27], v[158:161], v[180:183], v[24:27]
	v_mfma_f32_16x16x32_bf16 v[84:87], v[100:103], v[188:191], v[84:87]
	v_mfma_f32_16x16x32_bf16 v[20:23], v[158:161], v[188:191], v[20:23]
	v_mfma_f32_16x16x32_bf16 v[80:83], v[100:103], v[198:201], v[80:83]
	v_mfma_f32_16x16x32_bf16 v[16:19], v[158:161], v[198:201], v[16:19]
	s_barrier
	s_add_u32 s62, s66, 0x80080
	s_addc_u32 s63, s67, 0
	s_add_i32 s34, s35, s39
	v_lshl_add_u64 v[96:97], s[62:63], 0, v[146:147]
	s_mov_b32 m0, s34
	s_nop 0
	global_load_lds_dwordx4 v[96:97], off
	v_lshl_add_u64 v[96:97], s[62:63], 0, v[142:143]
	s_add_i32 m0, s34, 0x2000
	s_nop 0
	global_load_lds_dwordx4 v[96:97], off
	s_waitcnt vmcnt(6)
	s_barrier
	v_mfma_f32_16x16x32_bf16 v[76:79], v[208:211], v[162:165], v[76:79]
	v_mfma_f32_16x16x32_bf16 v[12:15], v[216:219], v[162:165], v[12:15]
	v_mfma_f32_16x16x32_bf16 v[68:71], v[208:211], v[170:173], v[68:71]
	v_mfma_f32_16x16x32_bf16 v[4:7], v[216:219], v[170:173], v[4:7]
	v_mfma_f32_16x16x32_bf16 v[72:75], v[208:211], v[184:187], v[72:75]
	v_mfma_f32_16x16x32_bf16 v[8:11], v[216:219], v[184:187], v[8:11]
	v_mfma_f32_16x16x32_bf16 v[64:67], v[208:211], v[192:195], v[64:67]
	v_mfma_f32_16x16x32_bf16 v[0:3], v[216:219], v[192:195], v[0:3]
	v_mfma_f32_16x16x32_bf16 v[76:79], v[212:215], v[166:169], v[76:79]
	v_mfma_f32_16x16x32_bf16 v[12:15], v[220:223], v[166:169], v[12:15]
	v_mfma_f32_16x16x32_bf16 v[68:71], v[212:215], v[180:183], v[68:71]
	v_mfma_f32_16x16x32_bf16 v[4:7], v[220:223], v[180:183], v[4:7]
	v_mfma_f32_16x16x32_bf16 v[72:75], v[212:215], v[188:191], v[72:75]
	v_mfma_f32_16x16x32_bf16 v[8:11], v[220:223], v[188:191], v[8:11]
	v_mfma_f32_16x16x32_bf16 v[64:67], v[212:215], v[198:201], v[64:67]
	v_mfma_f32_16x16x32_bf16 v[0:3], v[220:223], v[198:201], v[0:3]
	s_add_i32 s83, s83, 2
	s_add_u32 s81, s81, 0x100
	s_addc_u32 s82, s82, 0
	s_cmp_gt_u32 s83, 29
	s_mov_b64 s[62:63], s[64:65]
	s_barrier
	s_cbranch_scc0 .LBB0_173
	v_lshl_or_b32 v158, s70, 7, v150
	v_ashrrev_i32_e32 v159, 31, v158
	v_lshlrev_b64 v[96:97], 2, v[158:159]
	v_lshl_add_u64 v[98:99], s[30:31], 0, v[96:97]
	v_lshl_add_u64 v[100:101], s[46:47], 0, v[96:97]
	v_lshl_add_u64 v[102:103], s[24:25], 0, v[96:97]
	global_load_dwordx4 v[160:163], v[98:99], off
	global_load_dwordx4 v[170:173], v[100:101], off
	v_lshl_add_u64 v[98:99], s[42:43], 0, v[96:97]
	v_lshl_add_u64 v[100:101], s[48:49], 0, v[96:97]
	global_load_dwordx4 v[104:107], v[102:103], off
	global_load_dwordx4 v[164:167], v[98:99], off
	global_load_dwordx4 v[208:211], v[100:101], off
	v_lshl_add_u64 v[100:101], s[50:51], 0, v[96:97]
	global_load_dwordx4 v[212:215], v[100:101], off
	v_lshl_add_u64 v[98:99], s[26:27], 0, v[96:97]
	global_load_dwordx4 v[198:201], v[98:99], off
	v_lshl_add_u64 v[96:97], s[52:53], 0, v[96:97]
	global_load_dwordx4 v[216:219], v[96:97], off
	s_mov_b32 s62, 0xbf317218
	v_mov_b32_dpp v96, v126 row_ror:1 row_mask:0xf bank_mask:0xf
	v_mov_b32_dpp v97, v127 row_ror:1 row_mask:0xf bank_mask:0xf
	s_mov_b32 s34, 0xbfb8aa3b
	v_mov_b32_dpp v100, v138 row_ror:15 row_mask:0xf bank_mask:0xf
	v_mov_b32_dpp v101, v139 row_ror:15 row_mask:0xf bank_mask:0xf
	v_mov_b32_dpp v224, v112 row_ror:1 row_mask:0xf bank_mask:0xf
	v_mov_b32_dpp v225, v113 row_ror:1 row_mask:0xf bank_mask:0xf
	v_mov_b32_dpp v220, v128 row_ror:1 row_mask:0xf bank_mask:0xf
	v_mov_b32_dpp v221, v129 row_ror:1 row_mask:0xf bank_mask:0xf
	v_mov_b32_dpp v222, v140 row_ror:15 row_mask:0xf bank_mask:0xf
	v_mov_b32_dpp v223, v141 row_ror:15 row_mask:0xf bank_mask:0xf
	v_mov_b32_dpp v108, v110 row_ror:1 row_mask:0xf bank_mask:0xf
	v_mov_b32_dpp v180, v122 row_ror:15 row_mask:0xf bank_mask:0xf
	v_mov_b32_dpp v109, v111 row_ror:1 row_mask:0xf bank_mask:0xf
	v_mov_b32_dpp v181, v123 row_ror:15 row_mask:0xf bank_mask:0xf
	v_cmp_gt_i32_e32 vcc, 15, v151
	v_mov_b32_dpp v226, v124 row_ror:15 row_mask:0xf bank_mask:0xf
	v_mov_b32_dpp v227, v125 row_ror:15 row_mask:0xf bank_mask:0xf
	s_mov_b64 s[68:69], -1
	s_waitcnt vmcnt(0)
	v_pk_mul_f32 v[192:193], v[160:161], s[62:63] op_sel_hi:[1,0]
	v_pk_mul_f32 v[168:169], v[172:173], s[34:35] op_sel_hi:[1,0]
	v_pk_mul_f32 v[228:229], v[126:127], v[192:193]
	v_pk_mul_f32 v[194:195], v[162:163], s[62:63] op_sel_hi:[1,0]
	v_pk_mul_f32 v[186:187], v[104:105], s[62:63] op_sel_hi:[1,0]
	v_pk_mul_f32 v[188:189], v[166:167], s[62:63] op_sel_hi:[1,0]
	v_pk_mul_f32 v[172:173], v[210:211], s[34:35] op_sel_hi:[1,0]
	v_pk_mul_f32 v[96:97], v[186:187], v[96:97]
	v_pk_mul_f32 v[166:167], v[214:215], s[34:35] op_sel_hi:[1,0]
	v_pk_mul_f32 v[210:211], v[134:135], v[192:193]
	v_pk_mul_f32 v[214:215], v[130:131], v[192:193]
	v_pk_mul_f32 v[182:183], v[164:165], s[62:63] op_sel_hi:[1,0]
	v_pk_fma_f32 v[96:97], v[138:139], v[192:193], v[96:97]
	v_pk_fma_f32 v[210:211], v[138:139], v[186:187], v[210:211]
	v_pk_fma_f32 v[214:215], v[134:135], v[186:187], v[214:215]
	v_pk_fma_f32 v[228:229], v[130:131], v[186:187], v[228:229]
	v_pk_fma_f32 v[96:97], v[134:135], v[182:183], v[96:97]
	v_pk_fma_f32 v[210:211], v[130:131], v[182:183], v[210:211]
	v_pk_fma_f32 v[214:215], v[126:127], v[182:183], v[214:215]
	v_pk_fma_f32 v[100:101], v[182:183], v[100:101], v[228:229]
	v_pk_mul_f32 v[190:191], v[106:107], s[62:63] op_sel_hi:[1,0]
	v_pk_mul_f32 v[174:175], v[198:199], s[62:63] op_sel_hi:[1,0]
	v_pk_fma_f32 v[96:97], v[198:199], s[62:63], v[96:97] op_sel_hi:[1,0,1]
	v_pk_fma_f32 v[210:211], v[198:199], s[62:63], v[210:211] op_sel_hi:[1,0,1]
	v_pk_fma_f32 v[214:215], v[198:199], s[62:63], v[214:215] op_sel_hi:[1,0,1]
	v_pk_fma_f32 v[100:101], v[198:199], s[62:63], v[100:101] op_sel_hi:[1,0,1]
	v_pk_mul_f32 v[198:199], v[168:169], v[224:225]
	v_pk_mul_f32 v[164:165], v[170:171], s[34:35] op_sel_hi:[1,0]
	v_pk_mul_f32 v[170:171], v[208:209], s[34:35] op_sel_hi:[1,0]
	v_pk_mul_f32 v[162:163], v[212:213], s[34:35] op_sel_hi:[1,0]
	v_pk_mul_f32 v[104:105], v[190:191], v[220:221]
	v_pk_mul_f32 v[208:209], v[136:137], v[194:195]
	v_pk_mul_f32 v[212:213], v[132:133], v[194:195]
	v_pk_mul_f32 v[220:221], v[128:129], v[194:195]
	v_pk_fma_f32 v[198:199], v[124:125], v[172:173], v[198:199]
	v_pk_fma_f32 v[104:105], v[140:141], v[194:195], v[104:105]
	v_pk_fma_f32 v[208:209], v[140:141], v[190:191], v[208:209]
	v_pk_fma_f32 v[212:213], v[136:137], v[190:191], v[212:213]
	v_pk_fma_f32 v[220:221], v[132:133], v[190:191], v[220:221]
	v_pk_fma_f32 v[198:199], v[116:117], v[166:167], v[198:199]
	v_pk_mul_f32 v[232:233], v[110:111], v[170:171]
	v_pk_fma_f32 v[104:105], v[136:137], v[188:189], v[104:105]
	v_pk_fma_f32 v[208:209], v[132:133], v[188:189], v[208:209]
	v_pk_fma_f32 v[212:213], v[128:129], v[188:189], v[212:213]
	v_pk_fma_f32 v[220:221], v[188:189], v[222:223], v[220:221]
	v_pk_fma_f32 v[198:199], v[218:219], s[34:35], v[198:199] op_sel_hi:[1,0,1]
	v_pk_fma_f32 v[232:233], v[118:119], v[164:165], v[232:233]
	v_pk_mul_f32 v[184:185], v[200:201], s[62:63] op_sel_hi:[1,0]
	v_pk_fma_f32 v[104:105], v[200:201], s[62:63], v[104:105] op_sel_hi:[1,0,1]
	v_pk_fma_f32 v[208:209], v[200:201], s[62:63], v[208:209] op_sel_hi:[1,0,1]
	v_pk_fma_f32 v[212:213], v[200:201], s[62:63], v[212:213] op_sel_hi:[1,0,1]
	v_pk_fma_f32 v[200:201], v[200:201], s[62:63], v[220:221] op_sel_hi:[1,0,1]
	v_pk_mul_f32 v[108:109], v[164:165], v[108:109]
	v_pk_mul_f32 v[220:221], v[116:117], v[172:173]
	v_pk_mul_f32 v[222:223], v[114:115], v[170:171]
	v_pk_fma_f32 v[180:181], v[162:163], v[180:181], v[232:233]
	v_exp_f32_e32 v232, v198
	v_exp_f32_e32 v233, v199
	v_pk_fma_f32 v[108:109], v[122:123], v[170:171], v[108:109]
	v_pk_fma_f32 v[220:221], v[124:125], v[168:169], v[220:221]
	v_pk_fma_f32 v[222:223], v[122:123], v[164:165], v[222:223]
	v_pk_mul_f32 v[228:229], v[118:119], v[170:171]
	v_pk_fma_f32 v[108:109], v[114:115], v[162:163], v[108:109]
	v_pk_fma_f32 v[220:221], v[120:121], v[166:167], v[220:221]
	v_pk_fma_f32 v[222:223], v[118:119], v[162:163], v[222:223]
	v_pk_fma_f32 v[228:229], v[114:115], v[164:165], v[228:229]
	v_pk_mul_f32 v[230:231], v[112:113], v[172:173]
	v_pk_fma_f32 v[108:109], v[216:217], s[34:35], v[108:109] op_sel_hi:[1,0,1]
	v_pk_fma_f32 v[220:221], v[218:219], s[34:35], v[220:221] op_sel_hi:[1,0,1]
	v_pk_fma_f32 v[222:223], v[216:217], s[34:35], v[222:223] op_sel_hi:[1,0,1]
	v_pk_fma_f32 v[228:229], v[110:111], v[162:163], v[228:229]
	v_pk_fma_f32 v[230:231], v[120:121], v[168:169], v[230:231]
	v_pk_mul_f32 v[106:107], v[216:217], s[34:35] op_sel_hi:[1,0]
	v_pk_fma_f32 v[228:229], v[216:217], s[34:35], v[228:229] op_sel_hi:[1,0,1]
	v_pk_fma_f32 v[226:227], v[166:167], v[226:227], v[230:231]
	v_exp_f32_e32 v230, v108
	v_exp_f32_e32 v231, v109
	v_pk_fma_f32 v[180:181], v[216:217], s[34:35], v[180:181] op_sel_hi:[1,0,1]
	v_pk_add_f32 v[216:217], v[232:233], 1.0 op_sel_hi:[1,0]
	v_pk_mul_f32 v[104:105], v[104:105], v[198:199]
	v_pk_mul_f32 v[96:97], v[96:97], v[108:109]
	v_exp_f32_e32 v108, v222
	v_exp_f32_e32 v198, v220
	v_exp_f32_e32 v199, v221
	v_exp_f32_e32 v109, v223
	v_pk_mul_f32 v[224:225], v[120:121], v[172:173]
	v_rcp_f32_e32 v216, v216
	v_rcp_f32_e32 v217, v217
	v_pk_fma_f32 v[224:225], v[116:117], v[168:169], v[224:225]
	v_pk_add_f32 v[198:199], v[198:199], 1.0 op_sel_hi:[1,0]
	v_pk_fma_f32 v[224:225], v[112:113], v[166:167], v[224:225]
	v_pk_add_f32 v[108:109], v[108:109], 1.0 op_sel_hi:[1,0]
	v_pk_fma_f32 v[224:225], v[218:219], s[34:35], v[224:225] op_sel_hi:[1,0,1]
	v_pk_mul_f32 v[104:105], v[104:105], v[216:217]
	v_rcp_f32_e32 v108, v108
	v_rcp_f32_e32 v109, v109
	v_rcp_f32_e32 v198, v198
	v_rcp_f32_e32 v199, v199
	v_pk_mul_f32 v[208:209], v[208:209], v[220:221]
	v_exp_f32_e32 v216, v228
	v_exp_f32_e32 v220, v224
	v_exp_f32_e32 v221, v225
	v_exp_f32_e32 v217, v229
	v_pk_mul_f32 v[210:211], v[210:211], v[222:223]
	v_pk_mul_f32 v[160:161], v[218:219], s[34:35] op_sel_hi:[1,0]
	v_pk_fma_f32 v[218:219], v[218:219], s[34:35], v[226:227] op_sel_hi:[1,0,1]
	v_pk_mul_f32 v[198:199], v[208:209], v[198:199]
	v_pk_mul_f32 v[208:209], v[210:211], v[108:109]
	v_pk_add_f32 v[108:109], v[220:221], 1.0 op_sel_hi:[1,0]
	v_pk_add_f32 v[210:211], v[216:217], 1.0 op_sel_hi:[1,0]
	v_rcp_f32_e32 v108, v108
	v_rcp_f32_e32 v210, v210
	v_rcp_f32_e32 v211, v211
	v_rcp_f32_e32 v109, v109
	v_exp_f32_e32 v216, v180
	v_exp_f32_e32 v220, v218
	v_exp_f32_e32 v221, v219
	v_exp_f32_e32 v217, v181
	v_pk_add_f32 v[226:227], v[230:231], 1.0 op_sel_hi:[1,0]
	v_pk_mul_f32 v[212:213], v[212:213], v[224:225]
	v_pk_mul_f32 v[214:215], v[214:215], v[228:229]
	v_rcp_f32_e32 v226, v226
	v_rcp_f32_e32 v227, v227
	v_pk_mul_f32 v[212:213], v[212:213], v[108:109]
	v_pk_mul_f32 v[210:211], v[214:215], v[210:211]
	v_pk_add_f32 v[108:109], v[220:221], 1.0 op_sel_hi:[1,0]
	v_pk_add_f32 v[214:215], v[216:217], 1.0 op_sel_hi:[1,0]
	v_rcp_f32_e32 v108, v108
	v_rcp_f32_e32 v214, v214
	v_rcp_f32_e32 v109, v109
	v_rcp_f32_e32 v215, v215
	v_pk_mul_f32 v[96:97], v[96:97], v[226:227]
	v_pk_mul_f32 v[200:201], v[200:201], v[218:219]
	v_pk_mul_f32 v[100:101], v[100:101], v[180:181]
	v_pk_mul_f32 v[180:181], v[200:201], v[108:109]
	v_pk_mul_f32 v[200:201], v[100:101], v[214:215]
	v_cvt_pk_bf16_f32 v108, v96, v97
	v_cvt_pk_bf16_f32 v109, v104, v105
	v_cvt_pk_bf16_f32 v104, v208, v209
	v_cvt_pk_bf16_f32 v105, v198, v199
	v_cvt_pk_bf16_f32 v100, v210, v211
	v_cvt_pk_bf16_f32 v101, v212, v213
	s_nop 0
	v_cvt_pk_bf16_f32 v96, v200, v201
	v_cvt_pk_bf16_f32 v97, v180, v181
	s_and_saveexec_b64 s[62:63], vcc
	v_cmp_eq_u32_e32 vcc, 0, v151
	s_orn2_b64 s[68:69], vcc, exec
	s_or_b64 exec, exec, s[62:63]
	s_lshl_b32 s34, s79, 2
	s_lshl_b32 s62, s70, 8
	s_add_i32 s64, s34, s38
	s_ashr_i32 s63, s62, 31
	v_lshlrev_b32_e32 v176, 2, v150
	s_mov_b64 s[66:67], exec
	s_and_b64 s[68:69], s[66:67], s[68:69]
	v_mov_b32_e32 v198, 0xbf1f24be
	s_mov_b64 exec, s[68:69]
	s_cbranch_execz .LBB0_178
	s_ashr_i32 s65, s64, 31
	s_lshl_b64 s[68:69], s[64:65], 2
	v_or_b32_e32 v178, s68, v152
	v_mov_b64_e32 v[180:181], s[4:5]
	s_mov_b32 s29, 0xb000
	v_mad_u64_u32 v[180:181], s[70:71], v178, s29, v[180:181]
	v_mad_i32_i24 v181, s69, v204, v181
	v_lshl_add_u64 v[180:181], s[62:63], 2, v[180:181]
	v_lshl_add_u64 v[180:181], v[180:181], 0, v[176:177]
	v_cndmask_b32_e64 v133, v133, v141, s[8:9]
	v_cndmask_b32_e64 v132, v132, v140, s[8:9]
	v_cndmask_b32_e64 v131, v131, v139, s[8:9]
	v_cndmask_b32_e64 v130, v130, v138, s[8:9]
	v_cndmask_b32_e64 v118, v118, v122, s[8:9]
	v_cndmask_b32_e64 v121, v121, v125, s[8:9]
	v_cndmask_b32_e64 v120, v120, v124, s[8:9]
	v_cndmask_b32_e64 v119, v119, v123, s[8:9]
	global_store_dwordx4 v[180:181], v[130:133], off
	global_store_dwordx4 v[180:181], v[118:121], off offset:512
	v_cndmask_b32_e64 v125, v129, v137, s[8:9]
	v_cndmask_b32_e64 v124, v128, v136, s[8:9]
	v_add_co_u32_e32 v118, vcc, s29, v180
	v_cndmask_b32_e64 v123, v127, v135, s[8:9]
	v_cndmask_b32_e64 v122, v126, v134, s[8:9]
	v_addc_co_u32_e32 v119, vcc, 0, v181, vcc
	v_cndmask_b32_e64 v113, v113, v117, s[8:9]
	v_cndmask_b32_e64 v112, v112, v116, s[8:9]
	v_cndmask_b32_e64 v111, v111, v115, s[8:9]
	v_cndmask_b32_e64 v110, v110, v114, s[8:9]
	global_store_dwordx4 v[118:119], v[122:125], off
	global_store_dwordx4 v[118:119], v[110:113], off offset:512
.LBB0_178:
	s_or_b64 exec, exec, s[66:67]
	v_mov_b32_dpp v122, v66 row_ror:1 row_mask:0xf bank_mask:0xf
	v_mov_b32_dpp v123, v67 row_ror:1 row_mask:0xf bank_mask:0xf
	v_mov_b32_dpp v114, v64 row_ror:1 row_mask:0xf bank_mask:0xf
	v_mov_b32_dpp v115, v65 row_ror:1 row_mask:0xf bank_mask:0xf
	v_pk_mul_f32 v[136:137], v[80:81], v[192:193]
	v_pk_mul_f32 v[122:123], v[168:169], v[122:123]
	v_mov_b32_dpp v112, v92 row_ror:15 row_mask:0xf bank_mask:0xf
	v_mov_b32_dpp v113, v93 row_ror:15 row_mask:0xf bank_mask:0xf
	v_pk_fma_f32 v[136:137], v[84:85], v[186:187], v[136:137]
	v_pk_mul_f32 v[114:115], v[164:165], v[114:115]
	v_pk_fma_f32 v[122:123], v[78:79], v[172:173], v[122:123]
	v_pk_fma_f32 v[112:113], v[182:183], v[112:113], v[136:137]
	v_pk_fma_f32 v[114:115], v[76:77], v[170:171], v[114:115]
	v_pk_fma_f32 v[122:123], v[70:71], v[166:167], v[122:123]
	v_pk_mul_f32 v[136:137], v[68:69], v[170:171]
	v_pk_mul_f32 v[140:141], v[72:73], v[170:171]
	v_pk_mul_f32 v[170:171], v[64:65], v[170:171]
	v_mov_b32_dpp v116, v76 row_ror:15 row_mask:0xf bank_mask:0xf
	v_mov_b32_dpp v117, v77 row_ror:15 row_mask:0xf bank_mask:0xf
	v_pk_mul_f32 v[134:135], v[82:83], v[194:195]
	v_pk_add_f32 v[122:123], v[160:161], v[122:123]
	v_pk_fma_f32 v[136:137], v[76:77], v[164:165], v[136:137]
	v_pk_fma_f32 v[140:141], v[68:69], v[164:165], v[140:141]
	v_pk_fma_f32 v[164:165], v[72:73], v[164:165], v[170:171]
	v_mov_b32_dpp v110, v80 row_ror:1 row_mask:0xf bank_mask:0xf
	v_mov_b32_dpp v111, v81 row_ror:1 row_mask:0xf bank_mask:0xf
	v_mov_b32_dpp v118, v82 row_ror:1 row_mask:0xf bank_mask:0xf
	v_mov_b32_dpp v120, v94 row_ror:15 row_mask:0xf bank_mask:0xf
	v_mov_b32_dpp v119, v83 row_ror:1 row_mask:0xf bank_mask:0xf
	v_mov_b32_dpp v121, v95 row_ror:15 row_mask:0xf bank_mask:0xf
	v_pk_fma_f32 v[134:135], v[86:87], v[190:191], v[134:135]
	v_pk_fma_f32 v[116:117], v[162:163], v[116:117], v[164:165]
	v_exp_f32_e32 v164, v122
	v_exp_f32_e32 v165, v123
	v_pk_mul_f32 v[110:111], v[186:187], v[110:111]
	v_pk_mul_f32 v[118:119], v[190:191], v[118:119]
	v_pk_fma_f32 v[120:121], v[188:189], v[120:121], v[134:135]
	v_pk_mul_f32 v[134:135], v[70:71], v[172:173]
	v_pk_fma_f32 v[118:119], v[94:95], v[194:195], v[118:119]
	v_pk_fma_f32 v[110:111], v[92:93], v[192:193], v[110:111]
	v_pk_fma_f32 v[134:135], v[78:79], v[168:169], v[134:135]
	v_pk_fma_f32 v[110:111], v[88:89], v[182:183], v[110:111]
	v_pk_fma_f32 v[118:119], v[90:91], v[188:189], v[118:119]
	v_pk_fma_f32 v[114:115], v[68:69], v[162:163], v[114:115]
	v_pk_fma_f32 v[134:135], v[74:75], v[166:167], v[134:135]
	v_pk_fma_f32 v[136:137], v[72:73], v[162:163], v[136:137]
	v_pk_fma_f32 v[140:141], v[64:65], v[162:163], v[140:141]
	v_pk_add_f32 v[118:119], v[184:185], v[118:119]
	v_pk_add_f32 v[110:111], v[174:175], v[110:111]
	v_pk_add_f32 v[114:115], v[106:107], v[114:115]
	v_pk_add_f32 v[134:135], v[160:161], v[134:135]
	v_pk_add_f32 v[136:137], v[106:107], v[136:137]
	v_pk_add_f32 v[140:141], v[106:107], v[140:141]
	v_pk_add_f32 v[106:107], v[106:107], v[116:117]
	v_pk_add_f32 v[116:117], v[164:165], 1.0 op_sel_hi:[1,0]
	v_exp_f32_e32 v162, v114
	v_exp_f32_e32 v163, v115
	v_rcp_f32_e32 v116, v116
	v_rcp_f32_e32 v117, v117
	v_pk_mul_f32 v[110:111], v[110:111], v[114:115]
	v_pk_mul_f32 v[114:115], v[118:119], v[122:123]
	v_exp_f32_e32 v118, v136
	v_exp_f32_e32 v122, v134
	v_exp_f32_e32 v123, v135
	v_exp_f32_e32 v119, v137
	v_pk_mul_f32 v[126:127], v[90:91], v[194:195]
	v_pk_mul_f32 v[128:129], v[88:89], v[192:193]
	v_pk_mul_f32 v[138:139], v[74:75], v[172:173]
	v_pk_fma_f32 v[126:127], v[94:95], v[190:191], v[126:127]
	v_pk_fma_f32 v[128:129], v[92:93], v[186:187], v[128:129]
	v_pk_fma_f32 v[138:139], v[70:71], v[168:169], v[138:139]
	v_pk_fma_f32 v[126:127], v[86:87], v[188:189], v[126:127]
	v_pk_fma_f32 v[128:129], v[84:85], v[182:183], v[128:129]
	v_pk_fma_f32 v[138:139], v[66:67], v[166:167], v[138:139]
	v_pk_add_f32 v[126:127], v[184:185], v[126:127]
	v_pk_add_f32 v[128:129], v[174:175], v[128:129]
	v_pk_add_f32 v[138:139], v[160:161], v[138:139]
	v_pk_mul_f32 v[114:115], v[114:115], v[116:117]
	v_pk_add_f32 v[116:117], v[122:123], 1.0 op_sel_hi:[1,0]
	v_pk_add_f32 v[118:119], v[118:119], 1.0 op_sel_hi:[1,0]
	v_rcp_f32_e32 v116, v116
	v_rcp_f32_e32 v118, v118
	v_rcp_f32_e32 v119, v119
	v_rcp_f32_e32 v117, v117
	v_pk_mul_f32 v[122:123], v[126:127], v[134:135]
	v_pk_mul_f32 v[126:127], v[128:129], v[136:137]
	v_exp_f32_e32 v128, v140
	v_exp_f32_e32 v134, v138
	v_exp_f32_e32 v135, v139
	v_exp_f32_e32 v129, v141
	v_pk_mul_f32 v[130:131], v[86:87], v[194:195]
	v_pk_mul_f32 v[132:133], v[84:85], v[192:193]
	v_pk_mul_f32 v[172:173], v[66:67], v[172:173]
	v_mov_b32_dpp v124, v78 row_ror:15 row_mask:0xf bank_mask:0xf
	v_mov_b32_dpp v125, v79 row_ror:15 row_mask:0xf bank_mask:0xf
	v_pk_fma_f32 v[130:131], v[90:91], v[190:191], v[130:131]
	v_pk_fma_f32 v[132:133], v[88:89], v[186:187], v[132:133]
	v_pk_fma_f32 v[168:169], v[74:75], v[168:169], v[172:173]
	v_pk_fma_f32 v[130:131], v[82:83], v[188:189], v[130:131]
	v_pk_fma_f32 v[132:133], v[80:81], v[182:183], v[132:133]
	v_pk_fma_f32 v[124:125], v[166:167], v[124:125], v[168:169]
	v_pk_add_f32 v[130:131], v[184:185], v[130:131]
	v_pk_add_f32 v[132:133], v[174:175], v[132:133]
	v_pk_add_f32 v[124:125], v[160:161], v[124:125]
	v_pk_mul_f32 v[116:117], v[122:123], v[116:117]
	v_pk_mul_f32 v[118:119], v[126:127], v[118:119]
	v_pk_add_f32 v[122:123], v[134:135], 1.0 op_sel_hi:[1,0]
	v_pk_add_f32 v[126:127], v[128:129], 1.0 op_sel_hi:[1,0]
	v_rcp_f32_e32 v122, v122
	v_rcp_f32_e32 v126, v126
	v_rcp_f32_e32 v127, v127
	v_rcp_f32_e32 v123, v123
	v_pk_mul_f32 v[128:129], v[130:131], v[138:139]
	v_pk_mul_f32 v[130:131], v[132:133], v[140:141]
	v_exp_f32_e32 v132, v106
	v_exp_f32_e32 v134, v124
	v_exp_f32_e32 v135, v125
	v_exp_f32_e32 v133, v107
	v_pk_add_f32 v[160:161], v[162:163], 1.0 op_sel_hi:[1,0]
	v_pk_mul_f32 v[122:123], v[128:129], v[122:123]
	v_pk_mul_f32 v[126:127], v[130:131], v[126:127]
	v_pk_add_f32 v[128:129], v[134:135], 1.0 op_sel_hi:[1,0]
	v_pk_add_f32 v[130:131], v[132:133], 1.0 op_sel_hi:[1,0]
	v_rcp_f32_e32 v160, v160
	v_rcp_f32_e32 v161, v161
	v_rcp_f32_e32 v130, v130
	v_rcp_f32_e32 v128, v128
	v_rcp_f32_e32 v129, v129
	v_rcp_f32_e32 v131, v131
	v_pk_add_f32 v[120:121], v[184:185], v[120:121]
	v_pk_add_f32 v[112:113], v[174:175], v[112:113]
	v_pk_mul_f32 v[120:121], v[120:121], v[124:125]
	v_pk_mul_f32 v[106:107], v[112:113], v[106:107]
	v_cmp_gt_i32_e32 vcc, 15, v151
	s_mov_b64 s[70:71], -1
	v_pk_mul_f32 v[110:111], v[110:111], v[160:161]
	v_pk_mul_f32 v[128:129], v[120:121], v[128:129]
	v_pk_mul_f32 v[106:107], v[106:107], v[130:131]
	v_cvt_pk_bf16_f32 v124, v110, v111
	v_cvt_pk_bf16_f32 v125, v114, v115
	v_cvt_pk_bf16_f32 v120, v118, v119
	v_cvt_pk_bf16_f32 v121, v116, v117
	v_cvt_pk_bf16_f32 v116, v126, v127
	v_cvt_pk_bf16_f32 v117, v122, v123
	s_nop 0
	v_cvt_pk_bf16_f32 v112, v106, v107
	v_cvt_pk_bf16_f32 v113, v128, v129
	s_and_saveexec_b64 s[66:67], vcc
	v_cmp_eq_u32_e32 vcc, 0, v151
	s_orn2_b64 s[70:71], vcc, exec
	s_or_b64 exec, exec, s[66:67]
	s_add_i32 s66, s64, 2
	s_and_saveexec_b64 s[68:69], s[70:71]
	s_cbranch_execz .LBB0_182
	s_ashr_i32 s67, s66, 31
	s_lshl_b64 s[70:71], s[66:67], 2
	v_or_b32_e32 v110, s70, v152
	v_mov_b64_e32 v[106:107], s[4:5]
	s_mov_b32 s29, 0xb000
	v_mad_u64_u32 v[106:107], s[80:81], v110, s29, v[106:107]
	v_mad_i32_i24 v107, s71, v204, v107
	v_lshl_add_u64 v[106:107], s[62:63], 2, v[106:107]
	v_lshl_add_u64 v[106:107], v[106:107], 0, v[176:177]
	v_cndmask_b32_e64 v87, v87, v95, s[8:9]
	v_cndmask_b32_e64 v86, v86, v94, s[8:9]
	v_cndmask_b32_e64 v85, v85, v93, s[8:9]
	v_cndmask_b32_e64 v84, v84, v92, s[8:9]
	v_cndmask_b32_e64 v72, v72, v76, s[8:9]
	v_cndmask_b32_e64 v75, v75, v79, s[8:9]
	v_cndmask_b32_e64 v74, v74, v78, s[8:9]
	v_cndmask_b32_e64 v73, v73, v77, s[8:9]
	global_store_dwordx4 v[106:107], v[84:87], off
	global_store_dwordx4 v[106:107], v[72:75], off offset:512
	v_cndmask_b32_e64 v79, v83, v91, s[8:9]
	v_cndmask_b32_e64 v78, v82, v90, s[8:9]
	v_add_co_u32_e32 v72, vcc, s29, v106
	v_cndmask_b32_e64 v77, v81, v89, s[8:9]
	v_cndmask_b32_e64 v76, v80, v88, s[8:9]
	v_addc_co_u32_e32 v73, vcc, 0, v107, vcc
	v_cndmask_b32_e64 v67, v67, v71, s[8:9]
	v_cndmask_b32_e64 v66, v66, v70, s[8:9]
	v_cndmask_b32_e64 v65, v65, v69, s[8:9]
	v_cndmask_b32_e64 v64, v64, v68, s[8:9]
	global_store_dwordx4 v[72:73], v[76:79], off
	global_store_dwordx4 v[72:73], v[64:67], off offset:512
.LBB0_182:
	s_or_b64 exec, exec, s[68:69]
	v_or_b32_e32 v68, 4, v158
	v_ashrrev_i32_e32 v69, 31, v68
	v_lshlrev_b64 v[80:81], 2, v[68:69]
	global_load_dwordx4 v[64:67], v[102:103], off offset:16
	v_lshl_add_u64 v[68:69], s[30:31], 0, v[80:81]
	v_lshl_add_u64 v[82:83], s[48:49], 0, v[80:81]
	global_load_dwordx4 v[68:71], v[68:69], off
	v_lshl_add_u64 v[76:77], s[46:47], 0, v[80:81]
	global_load_dwordx4 v[130:133], v[82:83], off
	v_lshl_add_u64 v[82:83], s[50:51], 0, v[80:81]
	v_lshl_add_u64 v[72:73], s[42:43], 0, v[80:81]
	global_load_dwordx4 v[76:79], v[76:77], off
	v_lshl_add_u64 v[80:81], s[52:53], 0, v[80:81]
	global_load_dwordx4 v[134:137], v[82:83], off
	global_load_dwordx4 v[126:129], v[98:99], off offset:16
	global_load_dwordx4 v[138:141], v[80:81], off
	global_load_dwordx4 v[72:75], v[72:73], off
	s_mov_b32 s68, 0xbf317218
	v_mov_b32_dpp v88, v48 row_ror:1 row_mask:0xf bank_mask:0xf
	v_mov_b32_dpp v89, v49 row_ror:1 row_mask:0xf bank_mask:0xf
	s_mov_b32 s34, 0xbfb8aa3b
	v_mov_b32_dpp v90, v50 row_ror:1 row_mask:0xf bank_mask:0xf
	v_mov_b32_dpp v91, v51 row_ror:1 row_mask:0xf bank_mask:0xf
	v_mov_b32_dpp v98, v60 row_ror:15 row_mask:0xf bank_mask:0xf
	v_mov_b32_dpp v99, v61 row_ror:15 row_mask:0xf bank_mask:0xf
	v_mov_b32_dpp v102, v32 row_ror:1 row_mask:0xf bank_mask:0xf
	v_mov_b32_dpp v103, v33 row_ror:1 row_mask:0xf bank_mask:0xf
	v_mov_b32_dpp v110, v62 row_ror:15 row_mask:0xf bank_mask:0xf
	v_mov_b32_dpp v111, v63 row_ror:15 row_mask:0xf bank_mask:0xf
	v_mov_b32_dpp v114, v34 row_ror:1 row_mask:0xf bank_mask:0xf
	v_mov_b32_dpp v115, v35 row_ror:1 row_mask:0xf bank_mask:0xf
	v_mov_b32_dpp v118, v46 row_ror:15 row_mask:0xf bank_mask:0xf
	v_mov_b32_dpp v119, v47 row_ror:15 row_mask:0xf bank_mask:0xf
	v_mov_b32_dpp v106, v44 row_ror:15 row_mask:0xf bank_mask:0xf
	v_mov_b32_dpp v107, v45 row_ror:15 row_mask:0xf bank_mask:0xf
	v_cmp_gt_i32_e32 vcc, 15, v151
	s_mov_b64 s[70:71], -1
	s_waitcnt vmcnt(0)
	v_pk_mul_f32 v[84:85], v[64:65], s[68:69] op_sel_hi:[1,0]
	s_nop 0
	v_pk_mul_f32 v[160:161], v[84:85], v[88:89]
	v_pk_mul_f32 v[86:87], v[66:67], s[68:69] op_sel_hi:[1,0]
	v_pk_mul_f32 v[92:93], v[68:69], s[68:69] op_sel_hi:[1,0]
	v_pk_mul_f32 v[94:95], v[70:71], s[68:69] op_sel_hi:[1,0]
	v_pk_mul_f32 v[164:165], v[48:49], v[92:93]
	v_pk_mul_f32 v[122:123], v[86:87], v[90:91]
	v_pk_mul_f32 v[162:163], v[50:51], v[94:95]
	v_pk_mul_f32 v[70:71], v[76:77], s[34:35] op_sel_hi:[1,0]
	v_pk_mul_f32 v[76:77], v[130:131], s[34:35] op_sel_hi:[1,0]
	v_pk_mul_f32 v[68:69], v[134:135], s[34:35] op_sel_hi:[1,0]
	v_pk_fma_f32 v[130:131], v[60:61], v[92:93], v[160:161]
	v_pk_mul_f32 v[134:135], v[56:57], v[92:93]
	v_pk_mul_f32 v[160:161], v[52:53], v[92:93]
	v_pk_mul_f32 v[90:91], v[74:75], s[68:69] op_sel_hi:[1,0]
	v_pk_mul_f32 v[88:89], v[72:73], s[68:69] op_sel_hi:[1,0]
	v_pk_mul_f32 v[74:75], v[78:79], s[34:35] op_sel_hi:[1,0]
	v_pk_mul_f32 v[78:79], v[132:133], s[34:35] op_sel_hi:[1,0]
	v_pk_mul_f32 v[72:73], v[136:137], s[34:35] op_sel_hi:[1,0]
	v_pk_mul_f32 v[132:133], v[58:59], v[94:95]
	v_pk_mul_f32 v[136:137], v[54:55], v[94:95]
	v_pk_fma_f32 v[134:135], v[60:61], v[84:85], v[134:135]
	v_pk_fma_f32 v[160:161], v[56:57], v[84:85], v[160:161]
	v_pk_fma_f32 v[164:165], v[52:53], v[84:85], v[164:165]
	v_pk_fma_f32 v[122:123], v[62:63], v[94:95], v[122:123]
	v_pk_fma_f32 v[130:131], v[56:57], v[88:89], v[130:131]
	v_pk_fma_f32 v[132:133], v[62:63], v[86:87], v[132:133]
	v_pk_fma_f32 v[136:137], v[58:59], v[86:87], v[136:137]
	v_pk_fma_f32 v[134:135], v[52:53], v[88:89], v[134:135]
	v_pk_fma_f32 v[160:161], v[48:49], v[88:89], v[160:161]
	v_pk_fma_f32 v[162:163], v[54:55], v[86:87], v[162:163]
	v_pk_fma_f32 v[98:99], v[88:89], v[98:99], v[164:165]
	v_pk_mul_f32 v[80:81], v[126:127], s[68:69] op_sel_hi:[1,0]
	v_pk_fma_f32 v[122:123], v[58:59], v[90:91], v[122:123]
	v_pk_fma_f32 v[130:131], v[126:127], s[68:69], v[130:131] op_sel_hi:[1,0,1]
	v_pk_fma_f32 v[132:133], v[54:55], v[90:91], v[132:133]
	v_pk_fma_f32 v[136:137], v[50:51], v[90:91], v[136:137]
	v_pk_fma_f32 v[134:135], v[126:127], s[68:69], v[134:135] op_sel_hi:[1,0,1]
	v_pk_fma_f32 v[160:161], v[126:127], s[68:69], v[160:161] op_sel_hi:[1,0,1]
	v_pk_fma_f32 v[110:111], v[90:91], v[110:111], v[162:163]
	v_pk_fma_f32 v[98:99], v[126:127], s[68:69], v[98:99] op_sel_hi:[1,0,1]
	v_pk_mul_f32 v[102:103], v[70:71], v[102:103]
	v_pk_mul_f32 v[126:127], v[38:39], v[78:79]
	v_pk_mul_f32 v[82:83], v[128:129], s[68:69] op_sel_hi:[1,0]
	v_pk_fma_f32 v[122:123], v[128:129], s[68:69], v[122:123] op_sel_hi:[1,0,1]
	v_pk_fma_f32 v[132:133], v[128:129], s[68:69], v[132:133] op_sel_hi:[1,0,1]
	v_pk_fma_f32 v[136:137], v[128:129], s[68:69], v[136:137] op_sel_hi:[1,0,1]
	v_pk_fma_f32 v[110:111], v[128:129], s[68:69], v[110:111] op_sel_hi:[1,0,1]
	v_pk_mul_f32 v[114:115], v[74:75], v[114:115]
	v_pk_fma_f32 v[102:103], v[44:45], v[76:77], v[102:103]
	v_pk_mul_f32 v[128:129], v[36:37], v[76:77]
	v_pk_fma_f32 v[126:127], v[46:47], v[74:75], v[126:127]
	v_pk_fma_f32 v[114:115], v[46:47], v[78:79], v[114:115]
	v_pk_fma_f32 v[102:103], v[36:37], v[68:69], v[102:103]
	v_pk_fma_f32 v[128:129], v[44:45], v[70:71], v[128:129]
	v_pk_fma_f32 v[126:127], v[42:43], v[72:73], v[126:127]
	v_pk_mul_f32 v[166:167], v[34:35], v[78:79]
	v_pk_fma_f32 v[114:115], v[38:39], v[72:73], v[114:115]
	v_pk_fma_f32 v[102:103], v[138:139], s[34:35], v[102:103] op_sel_hi:[1,0,1]
	v_pk_fma_f32 v[128:129], v[40:41], v[68:69], v[128:129]
	v_pk_fma_f32 v[126:127], v[140:141], s[34:35], v[126:127] op_sel_hi:[1,0,1]
	v_pk_mul_f32 v[168:169], v[32:33], v[76:77]
	v_pk_fma_f32 v[166:167], v[42:43], v[74:75], v[166:167]
	v_pk_fma_f32 v[114:115], v[140:141], s[34:35], v[114:115] op_sel_hi:[1,0,1]
	v_pk_fma_f32 v[128:129], v[138:139], s[34:35], v[128:129] op_sel_hi:[1,0,1]
	v_pk_fma_f32 v[168:169], v[40:41], v[70:71], v[168:169]
	v_pk_fma_f32 v[118:119], v[72:73], v[118:119], v[166:167]
	v_exp_f32_e32 v166, v102
	v_exp_f32_e32 v167, v103
	v_pk_mul_f32 v[102:103], v[130:131], v[102:103]
	v_exp_f32_e32 v130, v126
	v_exp_f32_e32 v131, v127
	v_pk_mul_f32 v[164:165], v[40:41], v[76:77]
	v_pk_fma_f32 v[106:107], v[68:69], v[106:107], v[168:169]
	v_exp_f32_e32 v168, v114
	v_exp_f32_e32 v169, v115
	v_pk_mul_f32 v[114:115], v[122:123], v[114:115]
	v_exp_f32_e32 v122, v128
	v_exp_f32_e32 v123, v129
	v_pk_mul_f32 v[162:163], v[42:43], v[78:79]
	v_pk_fma_f32 v[164:165], v[36:37], v[70:71], v[164:165]
	v_pk_fma_f32 v[162:163], v[38:39], v[74:75], v[162:163]
	v_pk_fma_f32 v[164:165], v[32:33], v[68:69], v[164:165]
	v_pk_fma_f32 v[162:163], v[34:35], v[72:73], v[162:163]
	v_pk_fma_f32 v[164:165], v[138:139], s[34:35], v[164:165] op_sel_hi:[1,0,1]
	v_pk_add_f32 v[130:131], v[130:131], 1.0 op_sel_hi:[1,0]
	v_pk_fma_f32 v[162:163], v[140:141], s[34:35], v[162:163] op_sel_hi:[1,0,1]
	v_pk_add_f32 v[122:123], v[122:123], 1.0 op_sel_hi:[1,0]
	v_rcp_f32_e32 v130, v130
	v_rcp_f32_e32 v131, v131
	v_pk_mul_f32 v[126:127], v[132:133], v[126:127]
	v_exp_f32_e32 v132, v164
	v_exp_f32_e32 v133, v165
	v_pk_mul_f32 v[64:65], v[138:139], s[34:35] op_sel_hi:[1,0]
	v_pk_fma_f32 v[106:107], v[138:139], s[34:35], v[106:107] op_sel_hi:[1,0,1]
	v_pk_add_f32 v[138:139], v[168:169], 1.0 op_sel_hi:[1,0]
	v_rcp_f32_e32 v122, v122
	v_rcp_f32_e32 v123, v123
	v_pk_mul_f32 v[128:129], v[134:135], v[128:129]
	v_exp_f32_e32 v134, v162
	v_exp_f32_e32 v135, v163
	v_rcp_f32_e32 v138, v138
	v_rcp_f32_e32 v139, v139
	v_pk_mul_f32 v[126:127], v[126:127], v[130:131]
	v_pk_add_f32 v[130:131], v[132:133], 1.0 op_sel_hi:[1,0]
	v_pk_fma_f32 v[118:119], v[140:141], s[34:35], v[118:119] op_sel_hi:[1,0,1]
	v_pk_mul_f32 v[122:123], v[128:129], v[122:123]
	v_pk_add_f32 v[128:129], v[134:135], 1.0 op_sel_hi:[1,0]
	v_rcp_f32_e32 v130, v130
	v_rcp_f32_e32 v131, v131
	v_pk_mul_f32 v[132:133], v[136:137], v[162:163]
	v_exp_f32_e32 v136, v106
	v_exp_f32_e32 v137, v107
	v_pk_mul_f32 v[114:115], v[114:115], v[138:139]
	v_rcp_f32_e32 v128, v128
	v_rcp_f32_e32 v129, v129
	v_exp_f32_e32 v138, v118
	v_exp_f32_e32 v139, v119
	v_pk_mul_f32 v[134:135], v[160:161], v[164:165]
	v_pk_mul_f32 v[66:67], v[140:141], s[34:35] op_sel_hi:[1,0]
	v_pk_add_f32 v[140:141], v[166:167], 1.0 op_sel_hi:[1,0]
	v_pk_mul_f32 v[130:131], v[134:135], v[130:131]
	v_pk_add_f32 v[134:135], v[136:137], 1.0 op_sel_hi:[1,0]
	v_rcp_f32_e32 v140, v140
	v_rcp_f32_e32 v141, v141
	v_pk_mul_f32 v[128:129], v[132:133], v[128:129]
	v_pk_add_f32 v[132:133], v[138:139], 1.0 op_sel_hi:[1,0]
	v_rcp_f32_e32 v134, v134
	v_rcp_f32_e32 v135, v135
	v_rcp_f32_e32 v132, v132
	v_rcp_f32_e32 v133, v133
	v_pk_mul_f32 v[98:99], v[98:99], v[106:107]
	v_pk_mul_f32 v[102:103], v[102:103], v[140:141]
	v_pk_mul_f32 v[110:111], v[110:111], v[118:119]
	v_pk_mul_f32 v[98:99], v[98:99], v[134:135]
	v_pk_mul_f32 v[118:119], v[110:111], v[132:133]
	v_cvt_pk_bf16_f32 v110, v102, v103
	v_cvt_pk_bf16_f32 v111, v114, v115
	v_cvt_pk_bf16_f32 v106, v122, v123
	v_cvt_pk_bf16_f32 v107, v126, v127
	v_cvt_pk_bf16_f32 v102, v130, v131
	v_cvt_pk_bf16_f32 v103, v128, v129
	v_cvt_pk_bf16_f32 v98, v98, v99
	s_nop 0
	v_cvt_pk_bf16_f32 v99, v118, v119
	s_and_saveexec_b64 s[68:69], vcc
	v_cmp_eq_u32_e32 vcc, 0, v151
	s_orn2_b64 s[70:71], vcc, exec
	s_or_b64 exec, exec, s[68:69]
	s_and_saveexec_b64 s[68:69], s[70:71]
	s_cbranch_execz .LBB0_186
	s_ashr_i32 s65, s64, 31
	s_lshl_b64 s[64:65], s[64:65], 2
	v_or_b32_e32 v118, s64, v152
	v_mov_b64_e32 v[114:115], s[4:5]
	s_mov_b32 s29, 0xb000
	v_mad_u64_u32 v[114:115], s[70:71], v118, s29, v[114:115]
	v_mad_i32_i24 v115, s65, v204, v115
	v_lshl_add_u64 v[114:115], s[62:63], 2, v[114:115]
	v_lshl_add_u64 v[114:115], v[114:115], 0, v[176:177]
	v_cndmask_b32_e64 v55, v55, v63, s[8:9]
	v_cndmask_b32_e64 v54, v54, v62, s[8:9]
	v_cndmask_b32_e64 v53, v53, v61, s[8:9]
	v_cndmask_b32_e64 v52, v52, v60, s[8:9]
	v_cndmask_b32_e64 v40, v40, v44, s[8:9]
	v_cndmask_b32_e64 v43, v43, v47, s[8:9]
	v_cndmask_b32_e64 v42, v42, v46, s[8:9]
	v_cndmask_b32_e64 v41, v41, v45, s[8:9]
	global_store_dwordx4 v[114:115], v[52:55], off offset:16
	global_store_dwordx4 v[114:115], v[40:43], off offset:528
	v_cndmask_b32_e64 v47, v51, v59, s[8:9]
	v_cndmask_b32_e64 v46, v50, v58, s[8:9]
	v_add_co_u32_e32 v40, vcc, s29, v114
	v_cndmask_b32_e64 v45, v49, v57, s[8:9]
	v_cndmask_b32_e64 v44, v48, v56, s[8:9]
	v_addc_co_u32_e32 v41, vcc, 0, v115, vcc
	v_cndmask_b32_e64 v35, v35, v39, s[8:9]
	v_cndmask_b32_e64 v34, v34, v38, s[8:9]
	v_cndmask_b32_e64 v33, v33, v37, s[8:9]
	v_cndmask_b32_e64 v32, v32, v36, s[8:9]
	global_store_dwordx4 v[40:41], v[44:47], off offset:16
	global_store_dwordx4 v[40:41], v[32:35], off offset:528
.LBB0_186:
	s_or_b64 exec, exec, s[68:69]
	s_nop 0
	v_pk_mul_f32 v[56:57], v[18:19], v[94:95]
	v_pk_mul_f32 v[58:59], v[16:17], v[92:93]
	v_mov_b32_dpp v32, v16 row_ror:1 row_mask:0xf bank_mask:0xf
	v_mov_b32_dpp v34, v28 row_ror:15 row_mask:0xf bank_mask:0xf
	v_mov_b32_dpp v36, v0 row_ror:1 row_mask:0xf bank_mask:0xf
	v_mov_b32_dpp v33, v17 row_ror:1 row_mask:0xf bank_mask:0xf
	v_mov_b32_dpp v35, v29 row_ror:15 row_mask:0xf bank_mask:0xf
	v_mov_b32_dpp v37, v1 row_ror:1 row_mask:0xf bank_mask:0xf
	v_mov_b32_dpp v40, v18 row_ror:1 row_mask:0xf bank_mask:0xf
	v_mov_b32_dpp v42, v30 row_ror:15 row_mask:0xf bank_mask:0xf
	v_mov_b32_dpp v44, v2 row_ror:1 row_mask:0xf bank_mask:0xf
	v_mov_b32_dpp v41, v19 row_ror:1 row_mask:0xf bank_mask:0xf
	v_mov_b32_dpp v43, v31 row_ror:15 row_mask:0xf bank_mask:0xf
	v_mov_b32_dpp v45, v3 row_ror:1 row_mask:0xf bank_mask:0xf
	v_pk_fma_f32 v[56:57], v[22:23], v[86:87], v[56:57]
	v_pk_fma_f32 v[58:59], v[20:21], v[84:85], v[58:59]
	v_pk_mul_f32 v[32:33], v[84:85], v[32:33]
	v_pk_mul_f32 v[40:41], v[86:87], v[40:41]
	v_pk_fma_f32 v[42:43], v[90:91], v[42:43], v[56:57]
	v_pk_fma_f32 v[34:35], v[88:89], v[34:35], v[58:59]
	v_pk_mul_f32 v[36:37], v[70:71], v[36:37]
	v_pk_mul_f32 v[44:45], v[74:75], v[44:45]
	v_pk_mul_f32 v[56:57], v[6:7], v[78:79]
	v_pk_mul_f32 v[58:59], v[4:5], v[76:77]
	v_pk_fma_f32 v[40:41], v[30:31], v[94:95], v[40:41]
	v_pk_fma_f32 v[32:33], v[28:29], v[92:93], v[32:33]
	v_pk_fma_f32 v[44:45], v[14:15], v[78:79], v[44:45]
	v_pk_fma_f32 v[36:37], v[12:13], v[76:77], v[36:37]
	v_pk_fma_f32 v[56:57], v[14:15], v[74:75], v[56:57]
	v_pk_fma_f32 v[58:59], v[12:13], v[70:71], v[58:59]
	v_pk_fma_f32 v[32:33], v[24:25], v[88:89], v[32:33]
	v_pk_fma_f32 v[40:41], v[26:27], v[90:91], v[40:41]
	v_pk_fma_f32 v[36:37], v[4:5], v[68:69], v[36:37]
	v_pk_fma_f32 v[44:45], v[6:7], v[72:73], v[44:45]
	v_pk_fma_f32 v[56:57], v[10:11], v[72:73], v[56:57]
	v_pk_fma_f32 v[58:59], v[8:9], v[68:69], v[58:59]
	v_pk_mul_f32 v[62:63], v[8:9], v[76:77]
	v_pk_mul_f32 v[76:77], v[0:1], v[76:77]
	v_mov_b32_dpp v38, v12 row_ror:15 row_mask:0xf bank_mask:0xf
	v_mov_b32_dpp v39, v13 row_ror:15 row_mask:0xf bank_mask:0xf
	v_pk_add_f32 v[40:41], v[82:83], v[40:41]
	v_pk_add_f32 v[32:33], v[80:81], v[32:33]
	v_pk_add_f32 v[44:45], v[66:67], v[44:45]
	v_pk_add_f32 v[36:37], v[64:65], v[36:37]
	v_pk_add_f32 v[56:57], v[66:67], v[56:57]
	v_pk_add_f32 v[58:59], v[64:65], v[58:59]
	v_pk_fma_f32 v[62:63], v[4:5], v[70:71], v[62:63]
	v_pk_fma_f32 v[70:71], v[8:9], v[70:71], v[76:77]
	v_pk_fma_f32 v[62:63], v[0:1], v[68:69], v[62:63]
	v_pk_fma_f32 v[38:39], v[68:69], v[38:39], v[70:71]
	v_exp_f32_e32 v68, v36
	v_exp_f32_e32 v70, v44
	v_exp_f32_e32 v71, v45
	v_exp_f32_e32 v69, v37
	v_pk_mul_f32 v[32:33], v[32:33], v[36:37]
	v_pk_mul_f32 v[36:37], v[40:41], v[44:45]
	v_exp_f32_e32 v40, v58
	v_exp_f32_e32 v44, v56
	v_exp_f32_e32 v45, v57
	v_exp_f32_e32 v41, v59
	v_pk_mul_f32 v[48:49], v[26:27], v[94:95]
	v_pk_mul_f32 v[50:51], v[24:25], v[92:93]
	v_pk_mul_f32 v[60:61], v[10:11], v[78:79]
	v_pk_fma_f32 v[48:49], v[30:31], v[86:87], v[48:49]
	v_pk_fma_f32 v[50:51], v[28:29], v[84:85], v[50:51]
	v_pk_fma_f32 v[60:61], v[6:7], v[74:75], v[60:61]
	v_pk_fma_f32 v[48:49], v[22:23], v[90:91], v[48:49]
	v_pk_fma_f32 v[50:51], v[20:21], v[88:89], v[50:51]
	v_pk_fma_f32 v[60:61], v[2:3], v[72:73], v[60:61]
	v_pk_add_f32 v[48:49], v[82:83], v[48:49]
	v_pk_add_f32 v[50:51], v[80:81], v[50:51]
	v_pk_add_f32 v[60:61], v[66:67], v[60:61]
	v_pk_add_f32 v[62:63], v[64:65], v[62:63]
	v_pk_add_f32 v[44:45], v[44:45], 1.0 op_sel_hi:[1,0]
	v_pk_add_f32 v[40:41], v[40:41], 1.0 op_sel_hi:[1,0]
	v_rcp_f32_e32 v44, v44
	v_rcp_f32_e32 v40, v40
	v_rcp_f32_e32 v41, v41
	v_rcp_f32_e32 v45, v45
	v_pk_mul_f32 v[48:49], v[48:49], v[56:57]
	v_pk_mul_f32 v[50:51], v[50:51], v[58:59]
	v_exp_f32_e32 v56, v62
	v_exp_f32_e32 v58, v60
	v_exp_f32_e32 v59, v61
	v_exp_f32_e32 v57, v63
	v_pk_mul_f32 v[78:79], v[2:3], v[78:79]
	v_mov_b32_dpp v46, v14 row_ror:15 row_mask:0xf bank_mask:0xf
	v_mov_b32_dpp v47, v15 row_ror:15 row_mask:0xf bank_mask:0xf
	v_pk_fma_f32 v[74:75], v[10:11], v[74:75], v[78:79]
	v_pk_mul_f32 v[52:53], v[22:23], v[94:95]
	v_pk_fma_f32 v[46:47], v[72:73], v[46:47], v[74:75]
	v_pk_mul_f32 v[54:55], v[20:21], v[92:93]
	v_pk_add_f32 v[46:47], v[66:67], v[46:47]
	v_pk_add_f32 v[38:39], v[64:65], v[38:39]
	v_pk_mul_f32 v[44:45], v[48:49], v[44:45]
	v_pk_mul_f32 v[40:41], v[50:51], v[40:41]
	v_pk_add_f32 v[48:49], v[58:59], 1.0 op_sel_hi:[1,0]
	v_pk_add_f32 v[50:51], v[56:57], 1.0 op_sel_hi:[1,0]
	v_pk_fma_f32 v[52:53], v[26:27], v[86:87], v[52:53]
	v_pk_fma_f32 v[54:55], v[24:25], v[84:85], v[54:55]
	v_rcp_f32_e32 v50, v50
	v_rcp_f32_e32 v51, v51
	v_rcp_f32_e32 v48, v48
	v_rcp_f32_e32 v49, v49
	v_exp_f32_e32 v56, v38
	v_exp_f32_e32 v58, v46
	v_exp_f32_e32 v59, v47
	v_exp_f32_e32 v57, v39
	v_pk_fma_f32 v[52:53], v[18:19], v[90:91], v[52:53]
	v_pk_fma_f32 v[54:55], v[16:17], v[88:89], v[54:55]
	v_pk_add_f32 v[52:53], v[82:83], v[52:53]
	v_pk_add_f32 v[54:55], v[80:81], v[54:55]
	v_pk_mul_f32 v[52:53], v[52:53], v[60:61]
	v_pk_mul_f32 v[54:55], v[54:55], v[62:63]
	v_pk_add_f32 v[64:65], v[70:71], 1.0 op_sel_hi:[1,0]
	v_pk_add_f32 v[66:67], v[68:69], 1.0 op_sel_hi:[1,0]
	v_pk_mul_f32 v[48:49], v[52:53], v[48:49]
	v_pk_mul_f32 v[50:51], v[54:55], v[50:51]
	v_pk_add_f32 v[52:53], v[58:59], 1.0 op_sel_hi:[1,0]
	v_pk_add_f32 v[54:55], v[56:57], 1.0 op_sel_hi:[1,0]
	v_rcp_f32_e32 v66, v66
	v_rcp_f32_e32 v67, v67
	v_rcp_f32_e32 v64, v64
	v_rcp_f32_e32 v65, v65
	v_rcp_f32_e32 v54, v54
	v_rcp_f32_e32 v52, v52
	v_rcp_f32_e32 v53, v53
	v_rcp_f32_e32 v55, v55
	v_pk_add_f32 v[42:43], v[82:83], v[42:43]
	v_pk_add_f32 v[34:35], v[80:81], v[34:35]
	v_pk_mul_f32 v[42:43], v[42:43], v[46:47]
	v_pk_mul_f32 v[34:35], v[34:35], v[38:39]
	v_cmp_gt_i32_e32 vcc, 15, v151
	s_mov_b64 s[68:69], -1
	v_pk_mul_f32 v[36:37], v[36:37], v[64:65]
	v_pk_mul_f32 v[32:33], v[32:33], v[66:67]
	v_pk_mul_f32 v[38:39], v[42:43], v[52:53]
	v_pk_mul_f32 v[34:35], v[34:35], v[54:55]
	v_cvt_pk_bf16_f32 v126, v32, v33
	v_cvt_pk_bf16_f32 v127, v36, v37
	v_cvt_pk_bf16_f32 v122, v40, v41
	v_cvt_pk_bf16_f32 v123, v44, v45
	v_cvt_pk_bf16_f32 v118, v50, v51
	v_cvt_pk_bf16_f32 v119, v48, v49
	s_nop 0
	v_cvt_pk_bf16_f32 v114, v34, v35
	v_cvt_pk_bf16_f32 v115, v38, v39
	s_and_saveexec_b64 s[64:65], vcc
	v_cmp_eq_u32_e32 vcc, 0, v151
	s_orn2_b64 s[68:69], vcc, exec
	s_or_b64 exec, exec, s[64:65]
	s_and_saveexec_b64 s[64:65], s[68:69]
	s_cbranch_execz .LBB0_190
	s_ashr_i32 s67, s66, 31
	s_lshl_b64 s[66:67], s[66:67], 2
	v_or_b32_e32 v34, s66, v152
	v_mov_b64_e32 v[32:33], s[4:5]
	s_mov_b32 s29, 0xb000
	v_mad_u64_u32 v[32:33], s[68:69], v34, s29, v[32:33]
	v_mad_i32_i24 v33, s67, v204, v33
	v_lshl_add_u64 v[32:33], s[62:63], 2, v[32:33]
	v_lshl_add_u64 v[32:33], v[32:33], 0, v[176:177]
	v_cndmask_b32_e64 v23, v23, v31, s[8:9]
	v_cndmask_b32_e64 v22, v22, v30, s[8:9]
	v_cndmask_b32_e64 v21, v21, v29, s[8:9]
	v_cndmask_b32_e64 v20, v20, v28, s[8:9]
	v_cndmask_b32_e64 v8, v8, v12, s[8:9]
	v_cndmask_b32_e64 v11, v11, v15, s[8:9]
	v_cndmask_b32_e64 v10, v10, v14, s[8:9]
	v_cndmask_b32_e64 v9, v9, v13, s[8:9]
	global_store_dwordx4 v[32:33], v[20:23], off offset:16
	global_store_dwordx4 v[32:33], v[8:11], off offset:528
	v_cndmask_b32_e64 v15, v19, v27, s[8:9]
	v_cndmask_b32_e64 v14, v18, v26, s[8:9]
	v_add_co_u32_e32 v8, vcc, s29, v32
	v_cndmask_b32_e64 v13, v17, v25, s[8:9]
	v_cndmask_b32_e64 v12, v16, v24, s[8:9]
	v_addc_co_u32_e32 v9, vcc, 0, v33, vcc
	v_cndmask_b32_e64 v3, v3, v7, s[8:9]
	v_cndmask_b32_e64 v2, v2, v6, s[8:9]
	v_cndmask_b32_e64 v1, v1, v5, s[8:9]
	v_cndmask_b32_e64 v0, v0, v4, s[8:9]
	global_store_dwordx4 v[8:9], v[12:15], off offset:16
	global_store_dwordx4 v[8:9], v[0:3], off offset:528
